# 16 bytes of never-executed padding ahead of the GEMM main loop so that its head is 64-byte aligned (code-placement test on top of the mode-0 chained-address epilogue)
# baseline (speedup 1.0000x reference)
;     DI bool next(int i, Unit& u) const {
;     ...
;         int wgid = (int)L; { const int q = nwg / NXCD, r = nwg % NXCD, xcd = wgid % NXCD, off = wgid / NXCD; wgid = (xcd < r ? xcd * (q + 1) : r * (q + 1) + (xcd - r) * q) + off; }
;         if ((nM & (WGM - 1)) == 0) {
;             const int t = wgid >> 3, gid = (int)(((float)t + 0.5f) * invN);
;             u.pm = gid * WGM + (wgid & (WGM - 1)); u.pn = t - gid * nN; return true; }
;         const int nig = WGM * nN, gid = wgid / nig, fm = gid * WGM, gsz = (nM - fm) < WGM ? (nM - fm) : WGM;
;         u.pm = fm + ((wgid % nig) % gsz); u.pn = (wgid % nig) / gsz; return true;
.LBB0_785:
	s_abs_i32 s1, s3
	s_mul_hi_u32 s4, s1, s93
	s_mul_i32 s5, s4, s92
	s_ashr_i32 s0, s3, 31
	s_sub_i32 s1, s1, s5
	s_xor_b32 s0, s0, s54
	s_add_i32 s5, s4, 1
	s_sub_i32 s26, s1, s92
	s_cmp_ge_u32 s1, s92
	s_cselect_b32 s4, s5, s4
	s_cselect_b32 s1, s26, s1
	s_add_i32 s5, s4, 1
	s_cmp_ge_u32 s1, s92
	s_cselect_b32 s1, s5, s4
	s_xor_b32 s1, s1, s0
	s_sub_i32 s0, s1, s0
	s_lshl_b32 s1, s0, 3
	s_sub_i32 s4, s89, s1
	s_min_i32 s4, s4, 8
	s_abs_i32 s5, s4
	v_cvt_f32_u32_e32 v2, s5
	s_sub_i32 s28, 0, s5
	s_mul_i32 s0, s0, s43
	s_sub_i32 s0, s3, s0
	v_rcp_iflag_f32_e32 v2, v2
	s_abs_i32 s27, s0
	s_xor_b32 s26, s0, s4
	s_ashr_i32 s26, s26, 31
	v_mul_f32_e32 v2, 0x4f7ffffe, v2
	v_cvt_u32_f32_e32 v2, v2
	s_nop 0
	v_readfirstlane_b32 s29, v2
	s_mul_i32 s28, s28, s29
	s_mul_hi_u32 s28, s29, s28
	s_add_i32 s29, s29, s28
	s_mul_hi_u32 s28, s27, s29
	s_mul_i32 s29, s28, s5
	s_sub_i32 s27, s27, s29
	s_add_i32 s29, s28, 1
	s_sub_i32 s33, s27, s5
	s_cmp_ge_u32 s27, s5
	s_cselect_b32 s28, s29, s28
	s_cselect_b32 s27, s33, s27
	s_add_i32 s29, s28, 1
	s_cmp_ge_u32 s27, s5
	s_cselect_b32 s5, s29, s28
	s_xor_b32 s5, s5, s26
	s_sub_i32 s62, s5, s26
	s_mul_i32 s4, s62, s4
	s_sub_i32 s0, s0, s4
	s_add_i32 s63, s0, s1
	s_cbranch_execnz .LBB0_787
	s_nop 0
	s_nop 0
	s_nop 0
	s_nop 0
